# in-proj epilogue: dedicated straight-line path for gate tiles (pn>=8) instead of the generic per-block class dispatch; on top of rs state prefetch
# speedup vs baseline: 1.0165x; 1.0090x over previous
.LBB0_310:
	s_add_u32 s0, s18, 0xfffc0080
	s_addc_u32 s1, s19, -1
	s_add_i32 s27, 0, 0x10000
	v_add_u32_e32 v147, s27, v139
	ds_read_b128 v[152:155], v147
	ds_read_b128 v[156:159], v147 offset:1024
	ds_read_b128 v[160:163], v147 offset:2048
	ds_read_b128 v[164:167], v147 offset:3072
	s_cmp_eq_u32 s26, 12
	s_cselect_b32 s17, s3, s1
	s_cselect_b32 s16, s13, s0
	s_cselect_b32 s1, s20, s25
	s_cselect_b32 s0, s21, s24
	v_lshl_add_u64 v[190:191], s[18:19], 0, v[142:143]
	s_add_i32 m0, s95, 0xc000
	ds_read_b128 v[168:171], v181
	ds_read_b128 v[172:175], v181 offset:1024
	ds_read_b128 v[176:179], v181 offset:2048
	ds_read_b128 v[182:185], v181 offset:3072
	ds_read_b128 v[186:189], v181 offset:4096
	ds_read_b128 v[202:205], v181 offset:5120
	ds_read_b128 v[206:209], v181 offset:6144
	ds_read_b128 v[210:213], v181 offset:7168
	global_load_lds_dwordx4 v[190:191], off
	v_lshl_add_u64 v[190:191], s[18:19], 0, v[144:145]
	s_add_i32 m0, s95, 0xe000
	s_nop 0
	global_load_lds_dwordx4 v[190:191], off
	s_waitcnt lgkmcnt(8)
	s_barrier
	s_waitcnt lgkmcnt(0)
	s_setprio 1
	s_waitcnt lgkmcnt(0)
	v_mfma_f32_16x16x32_bf16 v[124:127], v[152:155], v[168:171], v[124:127]
	v_mfma_f32_16x16x32_bf16 v[120:123], v[160:163], v[168:171], v[120:123]
	v_mfma_f32_16x16x32_bf16 v[108:111], v[152:155], v[176:179], v[108:111]
	v_mfma_f32_16x16x32_bf16 v[104:107], v[160:163], v[176:179], v[104:107]
	v_mfma_f32_16x16x32_bf16 v[92:95], v[152:155], v[186:189], v[92:95]
	v_mfma_f32_16x16x32_bf16 v[88:91], v[160:163], v[186:189], v[88:91]
	v_mfma_f32_16x16x32_bf16 v[76:79], v[152:155], v[206:209], v[76:79]
	v_mfma_f32_16x16x32_bf16 v[72:75], v[160:163], v[206:209], v[72:75]
	v_mfma_f32_16x16x32_bf16 v[124:127], v[156:159], v[172:175], v[124:127]
	v_mfma_f32_16x16x32_bf16 v[120:123], v[164:167], v[172:175], v[120:123]
	v_mfma_f32_16x16x32_bf16 v[108:111], v[156:159], v[182:185], v[108:111]
	v_mfma_f32_16x16x32_bf16 v[104:107], v[164:167], v[182:185], v[104:107]
	v_mfma_f32_16x16x32_bf16 v[92:95], v[156:159], v[202:205], v[92:95]
	v_mfma_f32_16x16x32_bf16 v[88:91], v[164:167], v[202:205], v[88:91]
	v_mfma_f32_16x16x32_bf16 v[76:79], v[156:159], v[210:213], v[76:79]
	v_mfma_f32_16x16x32_bf16 v[72:75], v[164:167], v[210:213], v[72:75]
	s_setprio 0
	s_barrier
	s_add_i32 s36, 0, 0x14000
	s_add_i32 s27, s27, s94
	v_add_u32_e32 v147, s36, v139
	v_lshl_add_u64 v[190:191], s[0:1], 0, v[132:133]
	s_mov_b32 m0, s27
	ds_read_b128 v[214:217], v147
	ds_read_b128 v[218:221], v147 offset:1024
	ds_read_b128 v[238:241], v147 offset:2048
	ds_read_b128 v[242:245], v147 offset:3072
	global_load_lds_dwordx4 v[190:191], off
	v_lshl_add_u64 v[222:223], s[0:1], 0, v[128:129]
	s_add_i32 m0, s27, 0x2000
	s_nop 0
	global_load_lds_dwordx4 v[222:223], off
	s_barrier
	s_waitcnt lgkmcnt(0)
	s_setprio 1
	s_waitcnt lgkmcnt(0)
	v_mfma_f32_16x16x32_bf16 v[116:119], v[214:217], v[168:171], v[116:119]
	v_mfma_f32_16x16x32_bf16 v[112:115], v[238:241], v[168:171], v[112:115]
	v_mfma_f32_16x16x32_bf16 v[100:103], v[214:217], v[176:179], v[100:103]
	v_mfma_f32_16x16x32_bf16 v[96:99], v[238:241], v[176:179], v[96:99]
	v_mfma_f32_16x16x32_bf16 v[84:87], v[214:217], v[186:189], v[84:87]
	v_mfma_f32_16x16x32_bf16 v[80:83], v[238:241], v[186:189], v[80:83]
	v_mfma_f32_16x16x32_bf16 v[68:71], v[214:217], v[206:209], v[68:71]
	v_mfma_f32_16x16x32_bf16 v[64:67], v[238:241], v[206:209], v[64:67]
	v_mfma_f32_16x16x32_bf16 v[116:119], v[218:221], v[172:175], v[116:119]
	v_mfma_f32_16x16x32_bf16 v[112:115], v[242:245], v[172:175], v[112:115]
	v_mfma_f32_16x16x32_bf16 v[100:103], v[218:221], v[182:185], v[100:103]
	v_mfma_f32_16x16x32_bf16 v[96:99], v[242:245], v[182:185], v[96:99]
	v_mfma_f32_16x16x32_bf16 v[84:87], v[218:221], v[202:205], v[84:87]
	v_mfma_f32_16x16x32_bf16 v[80:83], v[242:245], v[202:205], v[80:83]
	v_mfma_f32_16x16x32_bf16 v[68:71], v[218:221], v[210:213], v[68:71]
	v_mfma_f32_16x16x32_bf16 v[64:67], v[242:245], v[210:213], v[64:67]
	s_setprio 0
	s_mov_b32 m0, s95
	v_lshl_add_u64 v[246:247], s[16:17], 0, v[134:135]
	s_barrier
	ds_read_b128 v[168:171], v181 offset:16384
	ds_read_b128 v[172:175], v181 offset:17408
	ds_read_b128 v[176:179], v181 offset:18432
	ds_read_b128 v[182:185], v181 offset:19456
	ds_read_b128 v[186:189], v181 offset:20480
	ds_read_b128 v[202:205], v181 offset:21504
	ds_read_b128 v[206:209], v181 offset:22528
	ds_read_b128 v[210:213], v181 offset:23552
	global_load_lds_dwordx4 v[246:247], off
	v_lshl_add_u64 v[248:249], s[16:17], 0, v[130:131]
	s_mov_b32 m0, s96
	s_nop 0
	global_load_lds_dwordx4 v[248:249], off
	s_barrier
	s_waitcnt lgkmcnt(0)
	s_setprio 1
	s_waitcnt lgkmcnt(0)
	v_mfma_f32_16x16x32_bf16 v[60:63], v[152:155], v[168:171], v[60:63]
	v_mfma_f32_16x16x32_bf16 v[56:59], v[160:163], v[168:171], v[56:59]
	v_mfma_f32_16x16x32_bf16 v[44:47], v[152:155], v[176:179], v[44:47]
	v_mfma_f32_16x16x32_bf16 v[40:43], v[160:163], v[176:179], v[40:43]
	v_mfma_f32_16x16x32_bf16 v[28:31], v[152:155], v[186:189], v[28:31]
	v_mfma_f32_16x16x32_bf16 v[24:27], v[160:163], v[186:189], v[24:27]
	v_mfma_f32_16x16x32_bf16 v[12:15], v[152:155], v[206:209], v[12:15]
	v_mfma_f32_16x16x32_bf16 v[8:11], v[160:163], v[206:209], v[8:11]
	v_mfma_f32_16x16x32_bf16 v[60:63], v[156:159], v[172:175], v[60:63]
	v_mfma_f32_16x16x32_bf16 v[56:59], v[164:167], v[172:175], v[56:59]
	v_mfma_f32_16x16x32_bf16 v[44:47], v[156:159], v[182:185], v[44:47]
	v_mfma_f32_16x16x32_bf16 v[40:43], v[164:167], v[182:185], v[40:43]
	v_mfma_f32_16x16x32_bf16 v[28:31], v[156:159], v[202:205], v[28:31]
	v_mfma_f32_16x16x32_bf16 v[24:27], v[164:167], v[202:205], v[24:27]
	v_mfma_f32_16x16x32_bf16 v[12:15], v[156:159], v[210:213], v[12:15]
	v_mfma_f32_16x16x32_bf16 v[8:11], v[164:167], v[210:213], v[8:11]
	s_setprio 0
	s_barrier
	s_add_u32 s28, s0, 0x40000
	s_addc_u32 s29, s1, 0
	s_add_i32 s27, s36, s94
	v_lshl_add_u64 v[152:153], s[28:29], 0, v[132:133]
	s_mov_b32 m0, s27
	s_nop 0
	global_load_lds_dwordx4 v[152:153], off
	v_lshl_add_u64 v[152:153], s[28:29], 0, v[128:129]
	s_add_i32 m0, s27, 0x2000
	s_nop 0
	global_load_lds_dwordx4 v[152:153], off
	s_waitcnt vmcnt(6)
	s_barrier
	s_setprio 1
	v_mfma_f32_16x16x32_bf16 v[52:55], v[214:217], v[168:171], v[52:55]
	v_mfma_f32_16x16x32_bf16 v[48:51], v[238:241], v[168:171], v[48:51]
	v_mfma_f32_16x16x32_bf16 v[36:39], v[214:217], v[176:179], v[36:39]
	v_mfma_f32_16x16x32_bf16 v[32:35], v[238:241], v[176:179], v[32:35]
	v_mfma_f32_16x16x32_bf16 v[20:23], v[214:217], v[186:189], v[20:23]
	v_mfma_f32_16x16x32_bf16 v[16:19], v[238:241], v[186:189], v[16:19]
	v_mfma_f32_16x16x32_bf16 v[4:7], v[214:217], v[206:209], v[4:7]
	v_mfma_f32_16x16x32_bf16 v[0:3], v[238:241], v[206:209], v[0:3]
	v_mfma_f32_16x16x32_bf16 v[52:55], v[218:221], v[172:175], v[52:55]
	v_mfma_f32_16x16x32_bf16 v[48:51], v[242:245], v[172:175], v[48:51]
	v_mfma_f32_16x16x32_bf16 v[36:39], v[218:221], v[182:185], v[36:39]
	v_mfma_f32_16x16x32_bf16 v[32:35], v[242:245], v[182:185], v[32:35]
	v_mfma_f32_16x16x32_bf16 v[20:23], v[218:221], v[202:205], v[20:23]
	v_mfma_f32_16x16x32_bf16 v[16:19], v[242:245], v[202:205], v[16:19]
	v_mfma_f32_16x16x32_bf16 v[4:7], v[218:221], v[210:213], v[4:7]
	v_mfma_f32_16x16x32_bf16 v[0:3], v[242:245], v[210:213], v[0:3]
	s_setprio 0
	s_add_i32 s27, 0, 0x18000
	v_add_u32_e32 v147, s27, v139
	s_barrier
	ds_read_b128 v[152:155], v147
	ds_read_b128 v[156:159], v147 offset:1024
	ds_read_b128 v[160:163], v147 offset:2048
	ds_read_b128 v[164:167], v147 offset:3072
	s_add_u32 s16, s16, 0x40000
	s_addc_u32 s17, s17, 0
	s_mov_b32 m0, s97
	v_lshl_add_u64 v[214:215], s[16:17], 0, v[134:135]
	ds_read_b128 v[168:171], v181 offset:32768
	ds_read_b128 v[172:175], v181 offset:33792
	ds_read_b128 v[176:179], v181 offset:34816
	ds_read_b128 v[182:185], v181 offset:35840
	ds_read_b128 v[186:189], v181 offset:36864
	ds_read_b128 v[202:205], v181 offset:37888
	ds_read_b128 v[206:209], v181 offset:38912
	ds_read_b128 v[210:213], v181 offset:39936
	global_load_lds_dwordx4 v[214:215], off
	v_lshl_add_u64 v[214:215], s[16:17], 0, v[130:131]
	s_mov_b32 m0, s4
	s_nop 0
	global_load_lds_dwordx4 v[214:215], off
	s_waitcnt lgkmcnt(8)
	s_barrier
	s_waitcnt lgkmcnt(0)
	s_setprio 1
	s_waitcnt lgkmcnt(0)
	v_mfma_f32_16x16x32_bf16 v[124:127], v[152:155], v[168:171], v[124:127]
	v_mfma_f32_16x16x32_bf16 v[120:123], v[160:163], v[168:171], v[120:123]
	v_mfma_f32_16x16x32_bf16 v[108:111], v[152:155], v[176:179], v[108:111]
	v_mfma_f32_16x16x32_bf16 v[104:107], v[160:163], v[176:179], v[104:107]
	v_mfma_f32_16x16x32_bf16 v[92:95], v[152:155], v[186:189], v[92:95]
	v_mfma_f32_16x16x32_bf16 v[88:91], v[160:163], v[186:189], v[88:91]
	v_mfma_f32_16x16x32_bf16 v[76:79], v[152:155], v[206:209], v[76:79]
	v_mfma_f32_16x16x32_bf16 v[72:75], v[160:163], v[206:209], v[72:75]
	v_mfma_f32_16x16x32_bf16 v[124:127], v[156:159], v[172:175], v[124:127]
	v_mfma_f32_16x16x32_bf16 v[120:123], v[164:167], v[172:175], v[120:123]
	v_mfma_f32_16x16x32_bf16 v[108:111], v[156:159], v[182:185], v[108:111]
	v_mfma_f32_16x16x32_bf16 v[104:107], v[164:167], v[182:185], v[104:107]
	v_mfma_f32_16x16x32_bf16 v[92:95], v[156:159], v[202:205], v[92:95]
	v_mfma_f32_16x16x32_bf16 v[88:91], v[164:167], v[202:205], v[88:91]
	v_mfma_f32_16x16x32_bf16 v[76:79], v[156:159], v[210:213], v[76:79]
	v_mfma_f32_16x16x32_bf16 v[72:75], v[164:167], v[210:213], v[72:75]
	s_setprio 0
	s_barrier
	s_add_i32 s16, 0, 0x1c000
	s_add_i32 s17, s27, s94
	v_add_u32_e32 v147, s16, v139
	v_lshl_add_u64 v[190:191], v[190:191], 0, s[30:31]
	s_mov_b32 m0, s17
	ds_read_b128 v[214:217], v147
	ds_read_b128 v[218:221], v147 offset:1024
	ds_read_b128 v[238:241], v147 offset:2048
	ds_read_b128 v[242:245], v147 offset:3072
	global_load_lds_dwordx4 v[190:191], off
	v_lshl_add_u64 v[190:191], v[222:223], 0, s[30:31]
	s_add_i32 m0, s17, 0x2000
	s_nop 0
	global_load_lds_dwordx4 v[190:191], off
	s_barrier
	s_waitcnt lgkmcnt(0)
	s_setprio 1
	s_waitcnt lgkmcnt(0)
	v_mfma_f32_16x16x32_bf16 v[116:119], v[214:217], v[168:171], v[116:119]
	v_mfma_f32_16x16x32_bf16 v[112:115], v[238:241], v[168:171], v[112:115]
	v_mfma_f32_16x16x32_bf16 v[100:103], v[214:217], v[176:179], v[100:103]
	v_mfma_f32_16x16x32_bf16 v[96:99], v[238:241], v[176:179], v[96:99]
	v_mfma_f32_16x16x32_bf16 v[84:87], v[214:217], v[186:189], v[84:87]
	v_mfma_f32_16x16x32_bf16 v[80:83], v[238:241], v[186:189], v[80:83]
	v_mfma_f32_16x16x32_bf16 v[68:71], v[214:217], v[206:209], v[68:71]
	v_mfma_f32_16x16x32_bf16 v[64:67], v[238:241], v[206:209], v[64:67]
	v_mfma_f32_16x16x32_bf16 v[116:119], v[218:221], v[172:175], v[116:119]
	v_mfma_f32_16x16x32_bf16 v[112:115], v[242:245], v[172:175], v[112:115]
	v_mfma_f32_16x16x32_bf16 v[100:103], v[218:221], v[182:185], v[100:103]
	v_mfma_f32_16x16x32_bf16 v[96:99], v[242:245], v[182:185], v[96:99]
	v_mfma_f32_16x16x32_bf16 v[84:87], v[218:221], v[202:205], v[84:87]
	v_mfma_f32_16x16x32_bf16 v[80:83], v[242:245], v[202:205], v[80:83]
	v_mfma_f32_16x16x32_bf16 v[68:71], v[218:221], v[210:213], v[68:71]
	v_mfma_f32_16x16x32_bf16 v[64:67], v[242:245], v[210:213], v[64:67]
	s_setprio 0
	s_mov_b32 m0, s6
	v_lshl_add_u64 v[190:191], v[246:247], 0, s[30:31]
	s_barrier
	ds_read_b128 v[168:171], v181 offset:49152
	ds_read_b128 v[172:175], v181 offset:50176
	ds_read_b128 v[176:179], v181 offset:51200
	ds_read_b128 v[182:185], v181 offset:52224
	ds_read_b128 v[186:189], v181 offset:53248
	ds_read_b128 v[202:205], v181 offset:54272
	ds_read_b128 v[206:209], v181 offset:55296
	ds_read_b128 v[210:213], v181 offset:56320
	global_load_lds_dwordx4 v[190:191], off
	v_lshl_add_u64 v[190:191], v[248:249], 0, s[30:31]
	s_mov_b32 m0, s7
	s_nop 0
	global_load_lds_dwordx4 v[190:191], off
	s_barrier
	s_waitcnt lgkmcnt(0)
	s_setprio 1
	s_waitcnt lgkmcnt(0)
	v_mfma_f32_16x16x32_bf16 v[60:63], v[152:155], v[168:171], v[60:63]
	v_mfma_f32_16x16x32_bf16 v[56:59], v[160:163], v[168:171], v[56:59]
	v_mfma_f32_16x16x32_bf16 v[44:47], v[152:155], v[176:179], v[44:47]
	v_mfma_f32_16x16x32_bf16 v[40:43], v[160:163], v[176:179], v[40:43]
	v_mfma_f32_16x16x32_bf16 v[28:31], v[152:155], v[186:189], v[28:31]
	v_mfma_f32_16x16x32_bf16 v[24:27], v[160:163], v[186:189], v[24:27]
	v_mfma_f32_16x16x32_bf16 v[12:15], v[152:155], v[206:209], v[12:15]
	v_mfma_f32_16x16x32_bf16 v[8:11], v[160:163], v[206:209], v[8:11]
	v_mfma_f32_16x16x32_bf16 v[60:63], v[156:159], v[172:175], v[60:63]
	v_mfma_f32_16x16x32_bf16 v[56:59], v[164:167], v[172:175], v[56:59]
	v_mfma_f32_16x16x32_bf16 v[44:47], v[156:159], v[182:185], v[44:47]
	v_mfma_f32_16x16x32_bf16 v[40:43], v[164:167], v[182:185], v[40:43]
	v_mfma_f32_16x16x32_bf16 v[28:31], v[156:159], v[202:205], v[28:31]
	v_mfma_f32_16x16x32_bf16 v[24:27], v[164:167], v[202:205], v[24:27]
	v_mfma_f32_16x16x32_bf16 v[12:15], v[156:159], v[210:213], v[12:15]
	v_mfma_f32_16x16x32_bf16 v[8:11], v[164:167], v[210:213], v[8:11]
	s_setprio 0
	s_barrier
	s_add_u32 s0, s0, 0x40080
	s_addc_u32 s1, s1, 0
	s_add_i32 s16, s16, s94
	v_lshl_add_u64 v[152:153], s[0:1], 0, v[132:133]
	s_mov_b32 m0, s16
	s_nop 0
	global_load_lds_dwordx4 v[152:153], off
	v_lshl_add_u64 v[152:153], s[0:1], 0, v[128:129]
	s_add_i32 m0, s16, 0x2000
	s_nop 0
	global_load_lds_dwordx4 v[152:153], off
	s_waitcnt vmcnt(6)
	s_barrier
	s_setprio 1
	v_mfma_f32_16x16x32_bf16 v[52:55], v[214:217], v[168:171], v[52:55]
	v_mfma_f32_16x16x32_bf16 v[48:51], v[238:241], v[168:171], v[48:51]
	v_mfma_f32_16x16x32_bf16 v[36:39], v[214:217], v[176:179], v[36:39]
	v_mfma_f32_16x16x32_bf16 v[32:35], v[238:241], v[176:179], v[32:35]
	v_mfma_f32_16x16x32_bf16 v[20:23], v[214:217], v[186:189], v[20:23]
	v_mfma_f32_16x16x32_bf16 v[16:19], v[238:241], v[186:189], v[16:19]
	v_mfma_f32_16x16x32_bf16 v[4:7], v[214:217], v[206:209], v[4:7]
	v_mfma_f32_16x16x32_bf16 v[0:3], v[238:241], v[206:209], v[0:3]
	v_mfma_f32_16x16x32_bf16 v[52:55], v[218:221], v[172:175], v[52:55]
	v_mfma_f32_16x16x32_bf16 v[48:51], v[242:245], v[172:175], v[48:51]
	v_mfma_f32_16x16x32_bf16 v[36:39], v[218:221], v[182:185], v[36:39]
	v_mfma_f32_16x16x32_bf16 v[32:35], v[242:245], v[182:185], v[32:35]
	v_mfma_f32_16x16x32_bf16 v[20:23], v[218:221], v[202:205], v[20:23]
	v_mfma_f32_16x16x32_bf16 v[16:19], v[242:245], v[202:205], v[16:19]
	v_mfma_f32_16x16x32_bf16 v[4:7], v[218:221], v[210:213], v[4:7]
	v_mfma_f32_16x16x32_bf16 v[0:3], v[242:245], v[210:213], v[0:3]
	s_setprio 0
	s_add_i32 s26, s26, 2
	s_add_u32 s18, s18, 0x100
	s_addc_u32 s19, s19, 0
	s_add_u32 s24, s24, 0x100
	s_addc_u32 s25, s25, 0
	s_cmp_gt_u32 s26, 13
	s_barrier
	s_cbranch_scc0 .LBB0_310
	s_cmp_lt_u32 s33, 8
	s_cbranch_scc1 .Lepi_generic
	s_lshl_b32 s16, s2, 19
	s_add_i32 s17, s33, -8
	s_lshl_b32 s17, s17, 13
	s_add_i32 s16, s16, s17
	s_add_u32 s16, s66, s16
	s_addc_u32 s17, s67, 0
	s_add_u32 s16, s16, 0x1c801000
	s_addc_u32 s17, s17, 0
	v_and_b32_e32 v152, 63, v224
	v_lshlrev_b32_e32 v152, 3, v152
	v_bfe_u32 v153, v224, 6, 2
	v_lshl_or_b32 v152, v153, 9, v152
	v_lshrrev_b32_e32 v153, 8, v224
	v_lshl_or_b32 v152, v153, 17, v152
	v_mov_b32_e32 v153, v152
	v_cvt_pk_bf16_f32 v154, v124, v125
	v_cvt_pk_bf16_f32 v155, v126, v127
	v_cvt_pk_bf16_f32 v156, v120, v121
	v_cvt_pk_bf16_f32 v157, v122, v123
	global_store_dwordx2 v153, v[154:155], s[16:17]
	global_store_dwordx2 v153, v[156:157], s[16:17] offset:2048
	v_add_u32_e32 v158, 0x1000, v152
	v_cvt_pk_bf16_f32 v160, v116, v117
	v_cvt_pk_bf16_f32 v161, v118, v119
	v_cvt_pk_bf16_f32 v162, v112, v113
	v_cvt_pk_bf16_f32 v163, v114, v115
	global_store_dwordx2 v158, v[160:161], s[16:17]
	global_store_dwordx2 v158, v[162:163], s[16:17] offset:2048
	v_add_u32_e32 v153, 0x8000, v152
	v_cvt_pk_bf16_f32 v154, v108, v109
	v_cvt_pk_bf16_f32 v155, v110, v111
	v_cvt_pk_bf16_f32 v156, v104, v105
	v_cvt_pk_bf16_f32 v157, v106, v107
	global_store_dwordx2 v153, v[154:155], s[16:17]
	global_store_dwordx2 v153, v[156:157], s[16:17] offset:2048
	v_add_u32_e32 v158, 0x9000, v152
	v_cvt_pk_bf16_f32 v160, v100, v101
	v_cvt_pk_bf16_f32 v161, v102, v103
	v_cvt_pk_bf16_f32 v162, v96, v97
	v_cvt_pk_bf16_f32 v163, v98, v99
	global_store_dwordx2 v158, v[160:161], s[16:17]
	global_store_dwordx2 v158, v[162:163], s[16:17] offset:2048
	v_add_u32_e32 v153, 0x10000, v152
	v_cvt_pk_bf16_f32 v154, v92, v93
	v_cvt_pk_bf16_f32 v155, v94, v95
	v_cvt_pk_bf16_f32 v156, v88, v89
	v_cvt_pk_bf16_f32 v157, v90, v91
	global_store_dwordx2 v153, v[154:155], s[16:17]
	global_store_dwordx2 v153, v[156:157], s[16:17] offset:2048
	v_add_u32_e32 v158, 0x11000, v152
	v_cvt_pk_bf16_f32 v160, v84, v85
	v_cvt_pk_bf16_f32 v161, v86, v87
	v_cvt_pk_bf16_f32 v162, v80, v81
	v_cvt_pk_bf16_f32 v163, v82, v83
	global_store_dwordx2 v158, v[160:161], s[16:17]
	global_store_dwordx2 v158, v[162:163], s[16:17] offset:2048
	v_add_u32_e32 v153, 0x18000, v152
	v_cvt_pk_bf16_f32 v154, v76, v77
	v_cvt_pk_bf16_f32 v155, v78, v79
	v_cvt_pk_bf16_f32 v156, v72, v73
	v_cvt_pk_bf16_f32 v157, v74, v75
	global_store_dwordx2 v153, v[154:155], s[16:17]
	global_store_dwordx2 v153, v[156:157], s[16:17] offset:2048
	v_add_u32_e32 v158, 0x19000, v152
	v_cvt_pk_bf16_f32 v160, v68, v69
	v_cvt_pk_bf16_f32 v161, v70, v71
	v_cvt_pk_bf16_f32 v162, v64, v65
	v_cvt_pk_bf16_f32 v163, v66, v67
	global_store_dwordx2 v158, v[160:161], s[16:17]
	global_store_dwordx2 v158, v[162:163], s[16:17] offset:2048
	v_add_u32_e32 v153, 0x40000, v152
	v_cvt_pk_bf16_f32 v154, v60, v61
	v_cvt_pk_bf16_f32 v155, v62, v63
	v_cvt_pk_bf16_f32 v156, v56, v57
	v_cvt_pk_bf16_f32 v157, v58, v59
	global_store_dwordx2 v153, v[154:155], s[16:17]
	global_store_dwordx2 v153, v[156:157], s[16:17] offset:2048
	v_add_u32_e32 v158, 0x41000, v152
	v_cvt_pk_bf16_f32 v160, v52, v53
	v_cvt_pk_bf16_f32 v161, v54, v55
	v_cvt_pk_bf16_f32 v162, v48, v49
	v_cvt_pk_bf16_f32 v163, v50, v51
	global_store_dwordx2 v158, v[160:161], s[16:17]
	global_store_dwordx2 v158, v[162:163], s[16:17] offset:2048
	v_add_u32_e32 v153, 0x48000, v152
	v_cvt_pk_bf16_f32 v154, v44, v45
	v_cvt_pk_bf16_f32 v155, v46, v47
	v_cvt_pk_bf16_f32 v156, v40, v41
	v_cvt_pk_bf16_f32 v157, v42, v43
	global_store_dwordx2 v153, v[154:155], s[16:17]
	global_store_dwordx2 v153, v[156:157], s[16:17] offset:2048
	v_add_u32_e32 v158, 0x49000, v152
	v_cvt_pk_bf16_f32 v160, v36, v37
	v_cvt_pk_bf16_f32 v161, v38, v39
	v_cvt_pk_bf16_f32 v162, v32, v33
	v_cvt_pk_bf16_f32 v163, v34, v35
	global_store_dwordx2 v158, v[160:161], s[16:17]
	global_store_dwordx2 v158, v[162:163], s[16:17] offset:2048
	v_add_u32_e32 v153, 0x50000, v152
	v_cvt_pk_bf16_f32 v154, v28, v29
	v_cvt_pk_bf16_f32 v155, v30, v31
	v_cvt_pk_bf16_f32 v156, v24, v25
	v_cvt_pk_bf16_f32 v157, v26, v27
	global_store_dwordx2 v153, v[154:155], s[16:17]
	global_store_dwordx2 v153, v[156:157], s[16:17] offset:2048
	v_add_u32_e32 v158, 0x51000, v152
	v_cvt_pk_bf16_f32 v160, v20, v21
	v_cvt_pk_bf16_f32 v161, v22, v23
	v_cvt_pk_bf16_f32 v162, v16, v17
	v_cvt_pk_bf16_f32 v163, v18, v19
	global_store_dwordx2 v158, v[160:161], s[16:17]
	global_store_dwordx2 v158, v[162:163], s[16:17] offset:2048
	v_add_u32_e32 v153, 0x58000, v152
	v_cvt_pk_bf16_f32 v154, v12, v13
	v_cvt_pk_bf16_f32 v155, v14, v15
	v_cvt_pk_bf16_f32 v156, v8, v9
	v_cvt_pk_bf16_f32 v157, v10, v11
	global_store_dwordx2 v153, v[154:155], s[16:17]
	global_store_dwordx2 v153, v[156:157], s[16:17] offset:2048
	v_add_u32_e32 v158, 0x59000, v152
	v_cvt_pk_bf16_f32 v160, v4, v5
	v_cvt_pk_bf16_f32 v161, v6, v7
	v_cvt_pk_bf16_f32 v162, v0, v1
	v_cvt_pk_bf16_f32 v163, v2, v3
	global_store_dwordx2 v158, v[160:161], s[16:17]
	global_store_dwordx2 v158, v[162:163], s[16:17] offset:2048
	s_mov_b64 s[2:3], exec
	s_branch .LBB0_306
.Lepi_generic:
	s_cmp_lt_i32 s2, 64
	s_cselect_b64 s[44:45], -1, 0
	s_lshl_b32 s26, s2, 8
	s_add_i32 s26, s26, s5
	s_add_i32 s0, s33, -2
	s_cmp_lt_u32 s0, 4
	s_mov_b64 s[24:25], s[66:67]
	s_cselect_b64 s[50:51], -1, 0
	s_cmp_gt_u32 s33, 3
	v_lshlrev_b32_e32 v162, 2, v138
	v_mov_b32_e32 v163, v197
	s_cselect_b64 s[42:43], -1, 0
	s_cmp_gt_u32 s0, 3
	v_lshl_add_u64 v[152:153], s[24:25], 0, v[162:163]
	s_mov_b64 s[0:1], 0x4500000
	v_bitop3_b32 v151, s26, v229, v137 bitop3:0xc8
	v_lshl_add_u64 v[156:157], v[152:153], 0, s[0:1]
	s_mov_b64 s[0:1], 0x4580800
	v_cndmask_b32_e64 v147, v141, v151, s[44:45]
	v_lshl_add_u64 v[154:155], v[152:153], 0, s[0:1]
	v_lshlrev_b32_e32 v196, 8, v147
	s_mov_b64 s[18:19], s[10:11]
	s_mov_b64 s[52:53], s[60:61]
	v_lshl_add_u64 v[170:171], v[156:157], 0, v[196:197]
	v_lshl_add_u64 v[172:173], v[154:155], 0, v[196:197]
	s_cbranch_scc1 .LBB0_313
	s_mov_b64 s[98:99], 0x1000
	s_mov_b64 s[100:101], 0x5000
	global_load_dwordx4 v[202:205], v[172:173], off
	global_load_dwordx4 v[206:209], v[170:171], off
	v_lshl_add_u64 v[218:219], v[172:173], 0, s[98:99]
	v_lshl_add_u64 v[220:221], v[170:171], 0, s[98:99]
	global_load_dwordx4 v[210:213], v[218:219], off
	global_load_dwordx4 v[214:217], v[220:221], off
	s_waitcnt vmcnt(2)
	v_pk_mul_f32 v[152:153], v[122:123], v[204:205]
	v_pk_mul_f32 v[168:169], v[120:121], v[202:203]
	v_pk_mul_f32 v[160:161], v[126:127], v[204:205]
	v_pk_mul_f32 v[158:159], v[124:125], v[202:203]
	v_pk_fma_f32 v[126:127], v[126:127], v[208:209], v[152:153] neg_lo:[0,0,1] neg_hi:[0,0,1]
	v_pk_fma_f32 v[124:125], v[124:125], v[206:207], v[168:169] neg_lo:[0,0,1] neg_hi:[0,0,1]
	v_pk_fma_f32 v[122:123], v[122:123], v[208:209], v[160:161]
	v_pk_fma_f32 v[120:121], v[120:121], v[206:207], v[158:159]
	v_pk_mul_f32 v[152:153], v[124:125], s[14:15] op_sel_hi:[1,0]
	v_pk_mul_f32 v[158:159], v[126:127], s[14:15] op_sel_hi:[1,0]
	v_pk_mul_f32 v[160:161], v[120:121], s[14:15] op_sel_hi:[1,0]
	v_pk_mul_f32 v[164:165], v[122:123], s[14:15] op_sel_hi:[1,0]
	v_cndmask_b32_e64 v121, v121, v161, s[42:43]
	v_cndmask_b32_e64 v123, v123, v165, s[42:43]
	v_cndmask_b32_e64 v122, v122, v164, s[42:43]
	v_cndmask_b32_e64 v120, v120, v160, s[42:43]
	v_cndmask_b32_e64 v127, v127, v159, s[42:43]
	v_cndmask_b32_e64 v126, v126, v158, s[42:43]
	v_cndmask_b32_e64 v125, v125, v153, s[42:43]
	v_cndmask_b32_e64 v124, v124, v152, s[42:43]
